# C pass: LDS-DMA staging (global_load_lds_dwordx4) into 4-slot XOR-swizzled unpadded ring, no ds_write staging
# speedup vs baseline: 1.0109x; 1.0109x over previous
; __device__ __forceinline__ float bf2f(unsigned short b) { return __uint_as_float((unsigned)b << 16); }
; template <int DV>
; __device__ __forceinline__ void attn_pass(const int tid, unsigned char* smem, const bf16_t* Q0, int qpitch, const bf16_t* Kb, int kpitch, const bf16_t* Vb, int vpitch,
;                                           int b, int ntiles, float kmax, f32x16 (&o)[DV / 32], float& linv) {
;     ...
;     const int lane = tid & 63, wid = __builtin_amdgcn_readfirstlane(tid >> 6), r32 = lane & 31, hi = lane >> 5;
;     bf16x8 qf[4];
;     { const bf16_t* qp = Q0 + (size_t)(wid * 32 + r32) * qpitch + 8 * hi;
; #pragma unroll
;       for (int ds = 0; ds < 4; ++ds) qf[ds] = *(const bf16x8*)(qp + 16 * ds); }
;     float ssq = 0.f;
; #pragma unroll
;     for (int ds = 0; ds < 4; ++ds)
; #pragma unroll
;         for (int j = 0; j < 8; ++j) { const float f = bf2f((unsigned short)qf[ds][j]); ssq += f * f; }
;     ssq = sum_x32(ssq);
;     const float nshift = -sqrtf(ssq) * kmax;
; #pragma unroll
;     for (int d0 = 0; d0 < DV / 32; ++d0)
; #pragma unroll
;         for (int r = 0; r < 16; ++r) o[d0][r] = 0.f;
;     float lsum = 0.f;
;     const int krow = tid >> 3, kch = tid & 7;
;     u32x4 kreg, vreg[NV];
;     auto tile_row = [&](int kt) -> size_t { return kt < 4 ? (size_t)(NLAT + 256 * b + 64 * kt) : (size_t)(SEQ * b + 64 * (kt - 4)); };
;     auto gload = [&](int kt) {
;         const size_t rb = tile_row(kt);
;         kreg = *(const u32x4*)(Kb + (rb + krow) * kpitch + 8 * kch);
; #pragma unroll
;         for (int i = 0; i < NV; ++i) { const int item = tid + 512 * i; const int vr = (DV == 64) ? (item >> 3) : (item >> 4), vc = (DV == 64) ? (item & 7) : (item & 15);
;             vreg[i] = *(const u32x4*)(Vb + (rb + vr) * vpitch + 8 * vc); }
;     };
;     auto lwrite = [&](int buf) {
;         unsigned char* Ks = smem + buf * BUF; unsigned char* Vs = Ks + KBYTES;
;         *(u32x4*)(Ks + krow * KP + 16 * kch) = kreg;
; #pragma unroll
;         for (int i = 0; i < NV; ++i) { const int item = tid + 512 * i; const int vr = (DV == 64) ? (item >> 3) : (item >> 4), vc = (DV == 64) ? (item & 7) : (item & 15);
;             *(u32x4*)(Vs + vr * VP + 16 * vc) = vreg[i]; }
;     };
;     gload(0); lwrite(0); __syncthreads();
.LBB0_405:
	s_xor_b64 s[14:15], s[16:17], -1
	s_lshl_b64 s[0:1], s[0:1], 1
	s_add_u32 s2, s28, s0
	s_addc_u32 s3, s29, s1
	s_add_u32 s16, s30, s0
	v_readfirstlane_b32 s0, v197
	s_addc_u32 s17, s31, s1
	s_ashr_i32 s0, s0, 1
	s_andn2_b32 s0, s0, 31
	v_or_b32_e32 v0, s0, v218
	v_ashrrev_i32_e32 v1, 31, v0
	v_lshlrev_b64 v[0:1], 11, v[0:1]
	v_lshl_add_u64 v[0:1], s[2:3], 0, v[0:1]
	v_lshl_add_u64 v[0:1], v[0:1], 0, v[192:193]
	global_load_dwordx4 v[96:99], v[0:1], off
	global_load_dwordx4 v[100:103], v[0:1], off offset:32
	global_load_dwordx4 v[104:107], v[0:1], off offset:64
	global_load_dwordx4 v[108:111], v[0:1], off offset:96
	s_mov_b32 s0, 0xf800000
	v_mov_b32_e32 v169, v193
	v_readlane_b32 s68, v251, 29
	v_readlane_b32 s69, v251, 30
	s_lshl_b32 s2, s26, 8
	s_add_u32 s68, s68, s2
	s_addc_u32 s69, s69, 0
	s_mov_b64 s[66:67], s[16:17]
	s_lshl_b32 s2, s10, 8
	s_add_i32 s65, s2, 0x8000
	s_lshl_b32 s2, s10, 13
	s_add_i32 s32, s2, 0xffffff00
	s_lshr_b32 s56, s27, 6
	s_lshl_b32 s56, s56, 10
	v_bfe_u32 v234, v136, 1, 3
	v_and_b32_e32 v235, 7, v197
	v_xor_b32_e32 v234, v234, v235
	v_lshlrev_b32_e32 v234, 4, v234
	v_lshl_add_u32 v166, v136, 10, v234
	v_and_b32_e32 v236, 3, v134
	v_lshlrev_b32_e32 v236, 2, v236
	v_and_b32_e32 v237, 15, v197
	v_xor_b32_e32 v236, v236, v237
	v_lshlrev_b32_e32 v236, 4, v236
	v_lshl_add_u32 v167, v134, 10, v236
	v_add_u32_e32 v132, 0x8000, v167
	s_mov_b32 s57, s56
	s_mov_b32 s70, 0
	s_cmp_lt_u32 s70, 4
	s_cselect_b32 s2, s65, s32
	s_lshl_b32 s3, s70, 6
	s_add_i32 s2, s2, s3
	s_lshl_b32 s2, s2, 10
	s_add_u32 s60, s66, s2
	s_addc_u32 s61, s67, 0
	s_cmp_lt_u32 s70, 4
	s_cselect_b32 s2, s65, s32
	s_lshl_b32 s3, s70, 6
	s_add_i32 s2, s2, s3
	s_lshl_b32 s2, s2, 10
	s_add_u32 s62, s68, s2
	s_addc_u32 s63, s69, 0
	s_mov_b32 m0, s57
	s_nop 0
	global_load_lds_dwordx4 v166, s[60:61]
	s_mov_b32 s70, 1
	s_cmp_lt_u32 s70, 4
	s_cselect_b32 s2, s65, s32
	s_lshl_b32 s3, s70, 6
	s_add_i32 s2, s2, s3
	s_lshl_b32 s2, s2, 10
	s_add_u32 s60, s66, s2
	s_addc_u32 s61, s67, 0
	s_add_i32 m0, s57, 0x6000
	s_nop 0
	global_load_lds_dwordx4 v166, s[60:61]
	s_add_i32 m0, s57, 0x8000
	s_nop 0
	global_load_lds_dwordx4 v167, s[62:63]
	s_add_i32 m0, s57, 0xa000
	s_nop 0
	global_load_lds_dwordx4 v132, s[62:63]
	s_cmp_lt_u32 s70, 4
	s_cselect_b32 s2, s65, s32
	s_lshl_b32 s3, s70, 6
	s_add_i32 s2, s2, s3
	s_lshl_b32 s2, s2, 10
	s_add_u32 s62, s68, s2
	s_addc_u32 s63, s69, 0
	s_mov_b32 s70, 2
	s_cmp_lt_u32 s70, 4
	s_cselect_b32 s2, s65, s32
	s_lshl_b32 s3, s70, 6
	s_add_i32 s2, s2, s3
	s_lshl_b32 s2, s2, 10
	s_add_u32 s60, s66, s2
	s_addc_u32 s61, s67, 0
	s_add_i32 m0, s57, 0xc000
	s_nop 0
	global_load_lds_dwordx4 v166, s[60:61]
	s_add_i32 m0, s57, 0xe000
	s_nop 0
	global_load_lds_dwordx4 v167, s[62:63]
	s_add_i32 m0, s57, 0x10000
	s_nop 0
	global_load_lds_dwordx4 v132, s[62:63]
	v_mov_b32_e32 v63, v193
	s_waitcnt vmcnt(10)
	v_and_b32_e32 v1, 0xffff0000, v96
	v_lshlrev_b32_e32 v0, 16, v96
	v_mul_f32_e32 v2, v1, v1
	v_fmac_f32_e32 v2, v0, v0
	v_lshlrev_b32_e32 v0, 16, v97
	v_fmac_f32_e32 v2, v0, v0
	v_and_b32_e32 v0, 0xffff0000, v97
	v_fmac_f32_e32 v2, v0, v0
	v_lshlrev_b32_e32 v0, 16, v98
	v_fmac_f32_e32 v2, v0, v0
	v_and_b32_e32 v0, 0xffff0000, v98
	v_fmac_f32_e32 v2, v0, v0
	v_lshlrev_b32_e32 v0, 16, v99
	v_fmac_f32_e32 v2, v0, v0
	v_and_b32_e32 v0, 0xffff0000, v99
	v_fmac_f32_e32 v2, v0, v0
	s_waitcnt vmcnt(9)
	v_lshlrev_b32_e32 v0, 16, v100
	v_fmac_f32_e32 v2, v0, v0
	v_and_b32_e32 v0, 0xffff0000, v100
	v_fmac_f32_e32 v2, v0, v0
	v_lshlrev_b32_e32 v0, 16, v101
	v_fmac_f32_e32 v2, v0, v0
	v_and_b32_e32 v0, 0xffff0000, v101
	v_fmac_f32_e32 v2, v0, v0
	v_lshlrev_b32_e32 v0, 16, v102
	v_fmac_f32_e32 v2, v0, v0
	v_and_b32_e32 v0, 0xffff0000, v102
	v_fmac_f32_e32 v2, v0, v0
	v_lshlrev_b32_e32 v0, 16, v103
	v_fmac_f32_e32 v2, v0, v0
	v_and_b32_e32 v0, 0xffff0000, v103
	v_fmac_f32_e32 v2, v0, v0
	s_waitcnt vmcnt(8)
	v_lshlrev_b32_e32 v0, 16, v104
	v_fmac_f32_e32 v2, v0, v0
	v_and_b32_e32 v0, 0xffff0000, v104
	v_fmac_f32_e32 v2, v0, v0
	v_lshlrev_b32_e32 v0, 16, v105
	v_fmac_f32_e32 v2, v0, v0
	v_and_b32_e32 v0, 0xffff0000, v105
	v_fmac_f32_e32 v2, v0, v0
	v_lshlrev_b32_e32 v0, 16, v106
	v_fmac_f32_e32 v2, v0, v0
	v_and_b32_e32 v0, 0xffff0000, v106
	v_fmac_f32_e32 v2, v0, v0
	v_lshlrev_b32_e32 v0, 16, v107
	v_fmac_f32_e32 v2, v0, v0
	v_and_b32_e32 v0, 0xffff0000, v107
	v_fmac_f32_e32 v2, v0, v0
	s_waitcnt vmcnt(7)
; template <int DV>
; __device__ __forceinline__ void attn_pass(const int tid, unsigned char* smem, const bf16_t* Q0, int qpitch, const bf16_t* Kb, int kpitch, const bf16_t* Vb, int vpitch,
;                                           int b, int ntiles, float kmax, f32x16 (&o)[DV / 32], float& linv) {
;     ...
;     float ssq = 0.f;
; #pragma unroll
;     for (int ds = 0; ds < 4; ++ds)
; #pragma unroll
;         for (int j = 0; j < 8; ++j) { const float f = bf2f((unsigned short)qf[ds][j]); ssq += f * f; }
;     ssq = sum_x32(ssq);
;     const float nshift = -sqrtf(ssq) * kmax;
; #pragma unroll
;     for (int d0 = 0; d0 < DV / 32; ++d0)
; #pragma unroll
;         for (int r = 0; r < 16; ++r) o[d0][r] = 0.f;
;     float lsum = 0.f;
;     const int krow = tid >> 3, kch = tid & 7;
;     u32x4 kreg, vreg[NV];
;     auto tile_row = [&](int kt) -> size_t { return kt < 4 ? (size_t)(NLAT + 256 * b + 64 * kt) : (size_t)(SEQ * b + 64 * (kt - 4)); };
;     auto gload = [&](int kt) {
;         const size_t rb = tile_row(kt);
;         kreg = *(const u32x4*)(Kb + (rb + krow) * kpitch + 8 * kch);
; #pragma unroll
;         for (int i = 0; i < NV; ++i) { const int item = tid + 512 * i; const int vr = (DV == 64) ? (item >> 3) : (item >> 4), vc = (DV == 64) ? (item & 7) : (item & 15);
;             vreg[i] = *(const u32x4*)(Vb + (rb + vr) * vpitch + 8 * vc); }
;     };
;     auto lwrite = [&](int buf) {
;         unsigned char* Ks = smem + buf * BUF; unsigned char* Vs = Ks + KBYTES;
;         *(u32x4*)(Ks + krow * KP + 16 * kch) = kreg;
; #pragma unroll
;         for (int i = 0; i < NV; ++i) { const int item = tid + 512 * i; const int vr = (DV == 64) ? (item >> 3) : (item >> 4), vc = (DV == 64) ? (item & 7) : (item & 15);
;             *(u32x4*)(Vs + vr * VP + 16 * vc) = vreg[i]; }
;     };
;     gload(0); lwrite(0); __syncthreads();
;     const int nhalf = (lane >> 4) & 1, q4 = (lane & 15) >> 2, p4 = lane & 3;
;     for (int kt = 0; kt < ntiles; ++kt) {
;         if (kt + 1 < ntiles) gload(kt + 1);
;         const unsigned char* Ks = smem + (kt & 1) * BUF; const unsigned char* Vs = Ks + KBYTES;
;         const unsigned char* kp = Ks + r32 * KP + hi * 16;
;         bf16x8 pf[2][2];
; #pragma unroll
;         for (int kb = 0; kb < 2; ++kb) {
;             f32x16 s;
; #pragma unroll
;             for (int r = 0; r < 16; ++r) s[r] = nshift;
; #pragma unroll
	v_lshlrev_b32_e32 v0, 16, v108
	v_fmac_f32_e32 v2, v0, v0
	v_and_b32_e32 v0, 0xffff0000, v108
	v_fmac_f32_e32 v2, v0, v0
	v_lshlrev_b32_e32 v0, 16, v109
	v_fmac_f32_e32 v2, v0, v0
	v_and_b32_e32 v0, 0xffff0000, v109
	v_fmac_f32_e32 v2, v0, v0
	v_and_b32_e32 v1, 0xffff0000, v110
	v_lshlrev_b32_e32 v0, 16, v110
	v_pk_mul_f32 v[0:1], v[0:1], v[0:1]
	s_nop 0
	v_add_f32_e32 v0, v0, v2
	v_add_f32_e32 v2, v1, v0
	v_and_b32_e32 v1, 0xffff0000, v111
	v_lshlrev_b32_e32 v0, 16, v111
	v_pk_mul_f32 v[0:1], v[0:1], v[0:1]
	s_nop 0
	v_add_f32_e32 v0, v0, v2
	v_add_f32_e32 v0, v1, v0
	v_mov_b32_e32 v1, v0
	s_nop 1
	v_permlane32_swap_b32_e32 v0, v1
	v_add_f32_e32 v0, v0, v1
	v_cmp_gt_f32_e32 vcc, s0, v0
	v_mul_f32_e32 v1, 0x4f800000, v0
	s_nop 0
	v_cndmask_b32_e32 v0, v0, v1, vcc
	v_sqrt_f32_e32 v1, v0
	s_nop 0
	v_add_u32_e32 v2, -1, v1
	v_fma_f32 v3, -v2, v1, v0
	v_cmp_ge_f32_e64 s[0:1], 0, v3
	v_add_u32_e32 v3, 1, v1
	s_nop 0
	v_cndmask_b32_e64 v2, v1, v2, s[0:1]
	v_fma_f32 v1, -v3, v1, v0
	v_cmp_lt_f32_e64 s[0:1], 0, v1
	s_nop 1
	v_cndmask_b32_e64 v1, v2, v3, s[0:1]
	v_mul_f32_e32 v2, 0x37800000, v1
	v_cndmask_b32_e32 v1, v1, v2, vcc
	v_cmp_class_f32_e32 vcc, v0, v227
	s_nop 1
	v_cndmask_b32_e32 v0, v1, v0, vcc
	v_mul_f32_e64 v32, v214, -v0
	v_mov_b32_e32 v33, v32
	v_mov_b32_e32 v34, v32
	v_mov_b32_e32 v35, v32
	v_mov_b32_e32 v36, v32
	v_mov_b32_e32 v37, v32
	v_mov_b32_e32 v38, v32
	v_mov_b32_e32 v39, v32
	v_mov_b32_e32 v40, v32
	v_mov_b32_e32 v41, v32
	v_mov_b32_e32 v42, v32
	v_mov_b32_e32 v43, v32
	v_mov_b32_e32 v44, v32
	v_mov_b32_e32 v45, v32
	v_mov_b32_e32 v46, v32
	v_mov_b32_e32 v47, v32
	v_mov_b32_e32 v0, 0
	v_mov_b32_e32 v1, 0
	v_mov_b32_e32 v2, 0
	v_mov_b32_e32 v3, 0
	v_mov_b32_e32 v4, 0
	v_mov_b32_e32 v5, 0
	v_mov_b32_e32 v6, 0
	v_mov_b32_e32 v7, 0
	v_mov_b32_e32 v8, 0
	v_mov_b32_e32 v9, 0
	v_mov_b32_e32 v10, 0
	v_mov_b32_e32 v11, 0
	v_mov_b32_e32 v12, 0
	v_mov_b32_e32 v13, 0
	v_mov_b32_e32 v14, 0
	v_mov_b32_e32 v15, 0
	v_mov_b32_e32 v16, 0
	v_mov_b32_e32 v17, 0
	v_mov_b32_e32 v18, 0
	v_mov_b32_e32 v19, 0
	v_mov_b32_e32 v20, 0
	v_mov_b32_e32 v21, 0
	v_mov_b32_e32 v22, 0
	v_mov_b32_e32 v23, 0
	v_mov_b32_e32 v24, 0
	v_mov_b32_e32 v25, 0
	v_mov_b32_e32 v26, 0
	v_mov_b32_e32 v27, 0
	v_mov_b32_e32 v28, 0
	v_mov_b32_e32 v29, 0
	v_mov_b32_e32 v30, 0
	v_mov_b32_e32 v31, 0
	v_mov_b32_e32 v48, 0
	v_mov_b32_e32 v49, 0
	v_mov_b32_e32 v50, 0
	v_mov_b32_e32 v51, 0
	v_mov_b32_e32 v52, 0
	v_mov_b32_e32 v53, 0
	v_mov_b32_e32 v54, 0
	v_mov_b32_e32 v55, 0
	v_mov_b32_e32 v56, 0
	v_mov_b32_e32 v57, 0
	v_mov_b32_e32 v58, 0
	v_mov_b32_e32 v59, 0
	v_mov_b32_e32 v60, 0
	v_mov_b32_e32 v61, 0
	v_mov_b32_e32 v62, 0
	v_mov_b32_e32 v63, 0
	v_mov_b32_e32 v64, 0
	v_mov_b32_e32 v65, 0
	v_mov_b32_e32 v66, 0
	v_mov_b32_e32 v67, 0
	v_mov_b32_e32 v68, 0
	v_mov_b32_e32 v69, 0
	v_mov_b32_e32 v70, 0
	v_mov_b32_e32 v71, 0
	v_mov_b32_e32 v72, 0
	v_mov_b32_e32 v73, 0
	v_mov_b32_e32 v74, 0
	v_mov_b32_e32 v75, 0
	v_mov_b32_e32 v76, 0
	v_mov_b32_e32 v77, 0
	v_mov_b32_e32 v78, 0
	v_mov_b32_e32 v79, 0
	v_mov_b32_e32 v169, 0
	v_bfe_u32 v234, v218, 1, 3
	v_lshrrev_b32_e32 v235, 4, v138
	v_xor_b32_e32 v234, v234, v235
	v_xor_b32_e32 v235, 0, v234
	v_lshlrev_b32_e32 v235, 4, v235
	v_lshl_or_b32 v174, v218, 7, v235
	v_xor_b32_e32 v235, 2, v234
	v_lshlrev_b32_e32 v235, 4, v235
	v_lshl_or_b32 v175, v218, 7, v235
	v_xor_b32_e32 v235, 4, v234
	v_lshlrev_b32_e32 v235, 4, v235
	v_lshl_or_b32 v210, v218, 7, v235
	v_xor_b32_e32 v235, 6, v234
	v_lshlrev_b32_e32 v235, 4, v235
	v_lshl_or_b32 v211, v218, 7, v235
	v_and_b32_e32 v236, 3, v215
	v_xor_b32_e32 v237, 0, v236
	v_lshl_add_u32 v237, v237, 6, v221
	v_lshl_add_u32 v142, v215, 8, v237
	v_xor_b32_e32 v237, 1, v236
	v_lshl_add_u32 v237, v237, 6, v221
	v_lshl_add_u32 v143, v215, 8, v237
	v_xor_b32_e32 v237, 2, v236
	v_lshl_add_u32 v237, v237, 6, v221
	v_lshl_add_u32 v146, v215, 8, v237
	v_xor_b32_e32 v237, 3, v236
	v_lshl_add_u32 v237, v237, 6, v221
	v_lshl_add_u32 v147, v215, 8, v237
	s_mov_b32 s59, 0
	s_waitcnt vmcnt(3)
	s_barrier
	ds_read_b128 v[198:201], v174
	ds_read_b128 v[202:205], v175
	ds_read_b128 v[206:209], v210
	ds_read_b128 v[150:153], v211
	s_waitcnt lgkmcnt(3)
	v_mfma_f32_32x32x16_bf16 v[80:95], v[198:201], v[96:99], v[32:47]
	ds_read_b128 v[198:201], v174 offset:4096
	s_add_i32 s71, s25, -1
	s_add_i32 s70, s59, 3
	s_min_u32 s70, s70, s71
	s_cmp_lt_u32 s70, 4
	s_cselect_b32 s2, s65, s32
	s_lshl_b32 s3, s70, 6
	s_add_i32 s2, s2, s3
	s_lshl_b32 s2, s2, 10
	s_add_u32 s60, s66, s2
	s_addc_u32 s61, s67, 0
	s_add_i32 s70, s59, 2
	s_min_u32 s70, s70, s71
	s_cmp_lt_u32 s70, 4
	s_cselect_b32 s2, s65, s32
	s_lshl_b32 s3, s70, 6
	s_add_i32 s2, s2, s3
	s_lshl_b32 s2, s2, 10
	s_add_u32 s62, s68, s2
	s_addc_u32 s63, s69, 0
	s_add_i32 s70, s59, 3
	s_and_b32 s70, s70, 3
	s_mul_i32 s70, s70, 0x6000
	s_add_i32 s57, s70, s56
	s_waitcnt lgkmcnt(3)
	v_mfma_f32_32x32x16_bf16 v[80:95], v[202:205], v[100:103], v[80:95]
	ds_read_b128 v[202:205], v175 offset:4096
	s_mov_b32 m0, s57
	s_nop 0
	global_load_lds_dwordx4 v166, s[60:61]
	s_waitcnt lgkmcnt(3)
	v_mfma_f32_32x32x16_bf16 v[80:95], v[206:209], v[104:107], v[80:95]
	ds_read_b128 v[206:209], v210 offset:4096
	s_add_i32 m0, s57, 0x2000
	s_nop 0
	global_load_lds_dwordx4 v167, s[62:63]
	s_add_i32 m0, s57, 0x4000
	s_nop 0
	global_load_lds_dwordx4 v132, s[62:63]
	s_and_b32 s2, s59, 3
	s_cmp_eq_u32 s2, 3
	s_cselect_b32 s2, 0x18000, 0
	s_sub_i32 s58, 0x6000, s2
	s_waitcnt lgkmcnt(3)
	v_mfma_f32_32x32x16_bf16 v[80:95], v[150:153], v[108:111], v[80:95]
	ds_read_b128 v[150:153], v211 offset:4096
	v_add_u32_e32 v174, s58, v174
	v_add_u32_e32 v175, s58, v175
	v_add_u32_e32 v210, s58, v210
	v_add_u32_e32 v211, s58, v211
	v_add_u32_e32 v142, s58, v142
	v_add_u32_e32 v143, s58, v143
	v_add_u32_e32 v146, s58, v146
	v_add_u32_e32 v147, s58, v147
	s_nop 7
	s_waitcnt lgkmcnt(3)
; template <int DV>
; __device__ __forceinline__ void attn_pass(const int tid, unsigned char* smem, const bf16_t* Q0, int qpitch, const bf16_t* Kb, int kpitch, const bf16_t* Vb, int vpitch,
;                                           int b, int ntiles, float kmax, f32x16 (&o)[DV / 32], float& linv) {
;     ...
;     for (int kt = 0; kt < ntiles; ++kt) {
;         if (kt + 1 < ntiles) gload(kt + 1);
;         const unsigned char* Ks = smem + (kt & 1) * BUF; const unsigned char* Vs = Ks + KBYTES;
;         const unsigned char* kp = Ks + r32 * KP + hi * 16;
;         bf16x8 pf[2][2];
; #pragma unroll
;         for (int kb = 0; kb < 2; ++kb) {
;             f32x16 s;
; #pragma unroll
;             for (int r = 0; r < 16; ++r) s[r] = nshift;
; #pragma unroll
;             for (int ds = 0; ds < 4; ++ds) {
;                 const bf16x8 kf = *(const bf16x8*)(kp + kb * 32 * KP + ds * 32);
;                 s = __builtin_amdgcn_mfma_f32_32x32x16_bf16(kf, qf[ds], s, 0, 0, 0);
;             }
;             float ls = 0.f;
; #pragma unroll
;             for (int r = 0; r < 16; ++r) { s[r] = __builtin_amdgcn_exp2f(s[r]); ls += s[r]; }
;             lsum += ls;
; #pragma unroll
;             for (int j = 0; j < 2; ++j) {
;                 u32x4 w0;
;                 w0.x = cvt_pk_bf16(s[8 * j + 0], s[8 * j + 1]); w0.y = cvt_pk_bf16(s[8 * j + 2], s[8 * j + 3]); w0.z = cvt_pk_bf16(s[8 * j + 4], s[8 * j + 5]); w0.w = cvt_pk_bf16(s[8 * j + 6], s[8 * j + 7]);
;                 pf[kb][j] = __builtin_bit_cast(bf16x8, w0);
;             }
;         }
;         const unsigned char* vp = Vs + (4 * hi + q4) * VP + (16 * nhalf + 4 * p4) * 2;
; #pragma unroll
;         for (int d0 = 0; d0 < DV / 32; ++d0) {
; #pragma unroll
;             for (int kb = 0; kb < 2; ++kb)
; #pragma unroll
;                 for (int j = 0; j < 2; ++j) {
;                     const unsigned char* a = vp + (32 * kb + 16 * j) * VP + d0 * 64;
;                     const s16x4 lo = ld_tr(a), h4 = ld_tr(a + 8 * VP);
;                     const bf16x8 vf = (bf16x8){lo[0], lo[1], lo[2], lo[3], h4[0], h4[1], h4[2], h4[3]};
;                     o[d0] = __builtin_amdgcn_mfma_f32_32x32x16_bf16(vf, pf[kb][j], o[d0], 0, 0, 0);
;                 }
;             if (d0 & 1) __builtin_amdgcn_sched_barrier(0);
;         }
;         if (kt + 1 < ntiles) lwrite((kt + 1) & 1);
;         __syncthreads();
;     }
	v_mfma_f32_32x32x16_bf16 v[112:127], v[198:201], v[96:99], v[32:47]
	ds_read_b128 v[198:201], v174
	ds_read_b64_tr_b16 v[154:155], v142 offset:8192
	ds_read_b64_tr_b16 v[156:157], v142 offset:10240
	v_exp_f32_e32 v80, v80
	v_exp_f32_e32 v81, v81
	v_exp_f32_e32 v82, v82
	v_add_f32_e32 v169, v169, v80
	v_exp_f32_e32 v83, v83
	v_add_f32_e32 v169, v169, v81
	v_cvt_pk_bf16_f32 v176, v80, v81
	v_exp_f32_e32 v84, v84
	v_add_f32_e32 v169, v169, v82
	v_exp_f32_e32 v85, v85
	v_add_f32_e32 v169, v169, v83
	v_cvt_pk_bf16_f32 v177, v82, v83
	v_exp_f32_e32 v86, v86
	s_waitcnt lgkmcnt(5)
	v_mfma_f32_32x32x16_bf16 v[112:127], v[202:205], v[100:103], v[112:127]
	ds_read_b128 v[202:205], v175
	ds_read_b64_tr_b16 v[158:159], v143 offset:8192
	ds_read_b64_tr_b16 v[160:161], v143 offset:10240
	v_add_f32_e32 v169, v169, v84
	v_exp_f32_e32 v87, v87
	v_add_f32_e32 v169, v169, v85
	v_cvt_pk_bf16_f32 v178, v84, v85
	v_exp_f32_e32 v88, v88
	v_add_f32_e32 v169, v169, v86
	v_exp_f32_e32 v89, v89
	v_add_f32_e32 v169, v169, v87
	v_cvt_pk_bf16_f32 v179, v86, v87
	v_exp_f32_e32 v90, v90
	v_add_f32_e32 v169, v169, v88
	v_exp_f32_e32 v91, v91
	v_add_f32_e32 v169, v169, v89
	s_waitcnt lgkmcnt(7)
	v_mfma_f32_32x32x16_bf16 v[112:127], v[206:209], v[104:107], v[112:127]
	ds_read_b128 v[206:209], v210
	ds_read_b64_tr_b16 v[162:163], v146 offset:8192
	ds_read_b64_tr_b16 v[164:165], v146 offset:10240
	v_cvt_pk_bf16_f32 v180, v88, v89
	v_exp_f32_e32 v92, v92
	v_add_f32_e32 v169, v169, v90
	v_exp_f32_e32 v93, v93
	v_add_f32_e32 v169, v169, v91
	v_cvt_pk_bf16_f32 v181, v90, v91
	v_exp_f32_e32 v94, v94
	v_add_f32_e32 v169, v169, v92
	v_exp_f32_e32 v95, v95
	v_add_f32_e32 v169, v169, v93
	v_cvt_pk_bf16_f32 v182, v92, v93
	v_add_f32_e32 v169, v169, v94
	v_add_f32_e32 v169, v169, v95
	v_cvt_pk_bf16_f32 v183, v94, v95
	s_waitcnt lgkmcnt(9)
	v_mfma_f32_32x32x16_bf16 v[112:127], v[150:153], v[108:111], v[112:127]
	ds_read_b128 v[150:153], v211
	ds_read_b64_tr_b16 v[230:231], v147 offset:8192
	ds_read_b64_tr_b16 v[232:233], v147 offset:10240
	s_add_i32 s59, s59, 1
	s_waitcnt vmcnt(3) lgkmcnt(0)
	s_barrier
.Lcattn_loop:
	v_mfma_f32_32x32x16_bf16 v[80:95], v[198:201], v[96:99], v[32:47]
	ds_read_b128 v[198:201], v174 offset:4096
	v_exp_f32_e32 v112, v112
	v_exp_f32_e32 v113, v113
	v_exp_f32_e32 v114, v114
	v_mfma_f32_32x32x16_bf16 v[80:95], v[202:205], v[100:103], v[80:95]
	ds_read_b128 v[202:205], v175 offset:4096
	v_add_f32_e32 v169, v169, v112
	v_exp_f32_e32 v115, v115
	v_add_f32_e32 v169, v169, v113
	v_cvt_pk_bf16_f32 v184, v112, v113
	v_mfma_f32_32x32x16_bf16 v[80:95], v[206:209], v[104:107], v[80:95]
	ds_read_b128 v[206:209], v210 offset:4096
	v_exp_f32_e32 v116, v116
	v_add_f32_e32 v169, v169, v114
	v_exp_f32_e32 v117, v117
	v_mfma_f32_32x32x16_bf16 v[80:95], v[150:153], v[108:111], v[80:95]
	ds_read_b128 v[150:153], v211 offset:4096
	v_add_f32_e32 v169, v169, v115
	v_cvt_pk_bf16_f32 v185, v114, v115
	v_exp_f32_e32 v118, v118
	v_add_f32_e32 v169, v169, v116
	s_waitcnt lgkmcnt(10)
	v_mfma_f32_32x32x16_bf16 v[0:15], v[154:157], v[176:179], v[0:15]
	ds_read_b64_tr_b16 v[154:155], v142 offset:12288
	ds_read_b64_tr_b16 v[156:157], v142 offset:14336
	s_add_i32 s71, s25, -1
	s_add_i32 s70, s59, 3
	s_min_u32 s70, s70, s71
	s_cmp_lt_u32 s70, 4
	s_cselect_b32 s2, s65, s32
	s_lshl_b32 s3, s70, 6
	s_add_i32 s2, s2, s3
	s_lshl_b32 s2, s2, 10
	s_add_u32 s60, s66, s2
	s_addc_u32 s61, s67, 0
	s_add_i32 s70, s59, 2
	s_min_u32 s70, s70, s71
	s_cmp_lt_u32 s70, 4
	s_cselect_b32 s2, s65, s32
	s_lshl_b32 s3, s70, 6
	s_add_i32 s2, s2, s3
	s_lshl_b32 s2, s2, 10
	s_add_u32 s62, s68, s2
	s_addc_u32 s63, s69, 0
	s_add_i32 s70, s59, 3
	s_and_b32 s70, s70, 3
	s_mul_i32 s70, s70, 0x6000
	s_add_i32 s57, s70, s56
	v_exp_f32_e32 v119, v119
	v_add_f32_e32 v169, v169, v117
	v_cvt_pk_bf16_f32 v186, v116, v117
	v_exp_f32_e32 v120, v120
	s_waitcnt lgkmcnt(10)
	v_mfma_f32_32x32x16_bf16 v[16:31], v[158:161], v[176:179], v[16:31]
	ds_read_b64_tr_b16 v[158:159], v143 offset:12288
	ds_read_b64_tr_b16 v[160:161], v143 offset:14336
	s_mov_b32 m0, s57
	s_nop 0
	global_load_lds_dwordx4 v166, s[60:61]
	v_add_f32_e32 v169, v169, v118
	v_exp_f32_e32 v121, v121
	v_add_f32_e32 v169, v169, v119
	s_waitcnt lgkmcnt(10)
	v_mfma_f32_32x32x16_bf16 v[48:63], v[162:165], v[176:179], v[48:63]
	ds_read_b64_tr_b16 v[162:163], v146 offset:12288
	ds_read_b64_tr_b16 v[164:165], v146 offset:14336
	s_add_i32 m0, s57, 0x2000
	s_nop 0
	global_load_lds_dwordx4 v167, s[62:63]
	s_add_i32 m0, s57, 0x4000
	s_nop 0
	global_load_lds_dwordx4 v132, s[62:63]
	v_cvt_pk_bf16_f32 v187, v118, v119
	v_exp_f32_e32 v122, v122
	v_add_f32_e32 v169, v169, v120
	v_exp_f32_e32 v123, v123
	s_waitcnt lgkmcnt(10)
	v_mfma_f32_32x32x16_bf16 v[64:79], v[230:233], v[176:179], v[64:79]
	ds_read_b64_tr_b16 v[230:231], v147 offset:12288
	ds_read_b64_tr_b16 v[232:233], v147 offset:14336
	s_and_b32 s2, s59, 3
	s_cmp_eq_u32 s2, 3
	s_cselect_b32 s2, 0x18000, 0
	s_sub_i32 s58, 0x6000, s2
	v_add_f32_e32 v169, v169, v121
	v_cvt_pk_bf16_f32 v188, v120, v121
	v_exp_f32_e32 v124, v124
	s_waitcnt lgkmcnt(6)
	v_mfma_f32_32x32x16_bf16 v[0:15], v[154:157], v[180:183], v[0:15]
	ds_read_b64_tr_b16 v[154:155], v142 offset:16384
	ds_read_b64_tr_b16 v[156:157], v142 offset:18432
	v_add_u32_e32 v174, s58, v174
	v_add_u32_e32 v175, s58, v175
	v_add_u32_e32 v210, s58, v210
	v_add_u32_e32 v211, s58, v211
	v_add_f32_e32 v169, v169, v122
	v_exp_f32_e32 v125, v125
	v_add_f32_e32 v169, v169, v123
	v_cvt_pk_bf16_f32 v189, v122, v123
	s_waitcnt lgkmcnt(6)
	v_mfma_f32_32x32x16_bf16 v[16:31], v[158:161], v[180:183], v[16:31]
	ds_read_b64_tr_b16 v[158:159], v143 offset:16384
	ds_read_b64_tr_b16 v[160:161], v143 offset:18432
	v_exp_f32_e32 v126, v126
	v_add_f32_e32 v169, v169, v124
	v_exp_f32_e32 v127, v127
	s_waitcnt lgkmcnt(6)
; template <int DV>
; __device__ __forceinline__ void attn_pass(const int tid, unsigned char* smem, const bf16_t* Q0, int qpitch, const bf16_t* Kb, int kpitch, const bf16_t* Vb, int vpitch,
;                                           int b, int ntiles, float kmax, f32x16 (&o)[DV / 32], float& linv) {
;     ...
;     for (int kt = 0; kt < ntiles; ++kt) {
;         if (kt + 1 < ntiles) gload(kt + 1);
;         const unsigned char* Ks = smem + (kt & 1) * BUF; const unsigned char* Vs = Ks + KBYTES;
;         const unsigned char* kp = Ks + r32 * KP + hi * 16;
;         bf16x8 pf[2][2];
; #pragma unroll
;         for (int kb = 0; kb < 2; ++kb) {
;             f32x16 s;
; #pragma unroll
;             for (int r = 0; r < 16; ++r) s[r] = nshift;
; #pragma unroll
;             for (int ds = 0; ds < 4; ++ds) {
;                 const bf16x8 kf = *(const bf16x8*)(kp + kb * 32 * KP + ds * 32);
;                 s = __builtin_amdgcn_mfma_f32_32x32x16_bf16(kf, qf[ds], s, 0, 0, 0);
;             }
;             float ls = 0.f;
; #pragma unroll
;             for (int r = 0; r < 16; ++r) { s[r] = __builtin_amdgcn_exp2f(s[r]); ls += s[r]; }
;             lsum += ls;
; #pragma unroll
;             for (int j = 0; j < 2; ++j) {
;                 u32x4 w0;
;                 w0.x = cvt_pk_bf16(s[8 * j + 0], s[8 * j + 1]); w0.y = cvt_pk_bf16(s[8 * j + 2], s[8 * j + 3]); w0.z = cvt_pk_bf16(s[8 * j + 4], s[8 * j + 5]); w0.w = cvt_pk_bf16(s[8 * j + 6], s[8 * j + 7]);
;                 pf[kb][j] = __builtin_bit_cast(bf16x8, w0);
;             }
;         }
;         const unsigned char* vp = Vs + (4 * hi + q4) * VP + (16 * nhalf + 4 * p4) * 2;
; #pragma unroll
;         for (int d0 = 0; d0 < DV / 32; ++d0) {
; #pragma unroll
;             for (int kb = 0; kb < 2; ++kb)
; #pragma unroll
;                 for (int j = 0; j < 2; ++j) {
;                     const unsigned char* a = vp + (32 * kb + 16 * j) * VP + d0 * 64;
;                     const s16x4 lo = ld_tr(a), h4 = ld_tr(a + 8 * VP);
;                     const bf16x8 vf = (bf16x8){lo[0], lo[1], lo[2], lo[3], h4[0], h4[1], h4[2], h4[3]};
;                     o[d0] = __builtin_amdgcn_mfma_f32_32x32x16_bf16(vf, pf[kb][j], o[d0], 0, 0, 0);
;                 }
;             if (d0 & 1) __builtin_amdgcn_sched_barrier(0);
;         }
;         if (kt + 1 < ntiles) lwrite((kt + 1) & 1);
;         __syncthreads();
;     }
	v_mfma_f32_32x32x16_bf16 v[48:63], v[162:165], v[180:183], v[48:63]
	ds_read_b64_tr_b16 v[162:163], v146 offset:16384
	ds_read_b64_tr_b16 v[164:165], v146 offset:18432
	v_add_f32_e32 v169, v169, v125
	v_cvt_pk_bf16_f32 v190, v124, v125
	v_add_f32_e32 v169, v169, v126
	v_add_f32_e32 v169, v169, v127
	v_cvt_pk_bf16_f32 v191, v126, v127
	s_waitcnt lgkmcnt(6)
	v_mfma_f32_32x32x16_bf16 v[64:79], v[230:233], v[180:183], v[64:79]
	ds_read_b64_tr_b16 v[230:231], v147 offset:16384
	ds_read_b64_tr_b16 v[232:233], v147 offset:18432
	v_mfma_f32_32x32x16_bf16 v[112:127], v[198:201], v[96:99], v[32:47]
	ds_read_b128 v[198:201], v174
	v_exp_f32_e32 v80, v80
	v_exp_f32_e32 v81, v81
	v_exp_f32_e32 v82, v82
	v_mfma_f32_32x32x16_bf16 v[112:127], v[202:205], v[100:103], v[112:127]
	ds_read_b128 v[202:205], v175
	v_add_f32_e32 v169, v169, v80
	v_exp_f32_e32 v83, v83
	v_add_f32_e32 v169, v169, v81
	v_cvt_pk_bf16_f32 v176, v80, v81
	v_mfma_f32_32x32x16_bf16 v[112:127], v[206:209], v[104:107], v[112:127]
	ds_read_b128 v[206:209], v210
	v_exp_f32_e32 v84, v84
	v_add_f32_e32 v169, v169, v82
	v_exp_f32_e32 v85, v85
	v_mfma_f32_32x32x16_bf16 v[112:127], v[150:153], v[108:111], v[112:127]
	ds_read_b128 v[150:153], v211
	v_add_f32_e32 v169, v169, v83
	v_cvt_pk_bf16_f32 v177, v82, v83
	v_exp_f32_e32 v86, v86
	v_add_f32_e32 v169, v169, v84
	s_waitcnt lgkmcnt(10)
	v_mfma_f32_32x32x16_bf16 v[0:15], v[154:157], v[184:187], v[0:15]
	ds_read_b64_tr_b16 v[154:155], v142 offset:20480
	ds_read_b64_tr_b16 v[156:157], v142 offset:22528
	v_exp_f32_e32 v87, v87
	v_add_f32_e32 v169, v169, v85
	v_cvt_pk_bf16_f32 v178, v84, v85
	v_exp_f32_e32 v88, v88
	s_waitcnt lgkmcnt(10)
	v_mfma_f32_32x32x16_bf16 v[16:31], v[158:161], v[184:187], v[16:31]
	ds_read_b64_tr_b16 v[158:159], v143 offset:20480
	ds_read_b64_tr_b16 v[160:161], v143 offset:22528
	v_add_f32_e32 v169, v169, v86
	v_exp_f32_e32 v89, v89
	v_add_f32_e32 v169, v169, v87
	s_waitcnt lgkmcnt(10)
	v_mfma_f32_32x32x16_bf16 v[48:63], v[162:165], v[184:187], v[48:63]
	ds_read_b64_tr_b16 v[162:163], v146 offset:20480
	ds_read_b64_tr_b16 v[164:165], v146 offset:22528
	v_cvt_pk_bf16_f32 v179, v86, v87
	v_exp_f32_e32 v90, v90
	v_add_f32_e32 v169, v169, v88
	v_exp_f32_e32 v91, v91
	s_waitcnt lgkmcnt(10)
	v_mfma_f32_32x32x16_bf16 v[64:79], v[230:233], v[184:187], v[64:79]
	ds_read_b64_tr_b16 v[230:231], v147 offset:20480
	ds_read_b64_tr_b16 v[232:233], v147 offset:22528
	v_add_u32_e32 v142, s58, v142
	v_add_u32_e32 v143, s58, v143
	v_add_u32_e32 v146, s58, v146
	v_add_u32_e32 v147, s58, v147
	v_add_f32_e32 v169, v169, v89
	v_cvt_pk_bf16_f32 v180, v88, v89
	v_exp_f32_e32 v92, v92
	s_waitcnt lgkmcnt(6)
	v_mfma_f32_32x32x16_bf16 v[0:15], v[154:157], v[188:191], v[0:15]
	ds_read_b64_tr_b16 v[154:155], v142 offset:8192
	ds_read_b64_tr_b16 v[156:157], v142 offset:10240
	v_add_f32_e32 v169, v169, v90
	v_exp_f32_e32 v93, v93
	v_add_f32_e32 v169, v169, v91
	v_cvt_pk_bf16_f32 v181, v90, v91
	s_waitcnt lgkmcnt(6)
	v_mfma_f32_32x32x16_bf16 v[16:31], v[158:161], v[188:191], v[16:31]
	ds_read_b64_tr_b16 v[158:159], v143 offset:8192
	ds_read_b64_tr_b16 v[160:161], v143 offset:10240
	v_exp_f32_e32 v94, v94
	v_add_f32_e32 v169, v169, v92
	v_exp_f32_e32 v95, v95
	s_waitcnt lgkmcnt(6)
	v_mfma_f32_32x32x16_bf16 v[48:63], v[162:165], v[188:191], v[48:63]
	ds_read_b64_tr_b16 v[162:163], v146 offset:8192
	ds_read_b64_tr_b16 v[164:165], v146 offset:10240
	s_add_i32 s59, s59, 1
	v_add_f32_e32 v169, v169, v93
	v_cvt_pk_bf16_f32 v182, v92, v93
	v_add_f32_e32 v169, v169, v94
	v_add_f32_e32 v169, v169, v95
	v_cvt_pk_bf16_f32 v183, v94, v95
	s_waitcnt lgkmcnt(6)
	v_mfma_f32_32x32x16_bf16 v[64:79], v[230:233], v[188:191], v[64:79]
	ds_read_b64_tr_b16 v[230:231], v147 offset:8192
	ds_read_b64_tr_b16 v[232:233], v147 offset:10240
	s_add_i32 s71, s25, -1
	s_cmp_lt_u32 s59, s71
	s_waitcnt vmcnt(3) lgkmcnt(8)
	s_barrier
	s_cbranch_scc1 .Lcattn_loop
	v_mfma_f32_32x32x16_bf16 v[80:95], v[198:201], v[96:99], v[32:47]
	ds_read_b128 v[198:201], v174 offset:4096
	v_exp_f32_e32 v112, v112
	v_exp_f32_e32 v113, v113
	v_exp_f32_e32 v114, v114
	v_mfma_f32_32x32x16_bf16 v[80:95], v[202:205], v[100:103], v[80:95]
	ds_read_b128 v[202:205], v175 offset:4096
	v_add_f32_e32 v169, v169, v112
	v_exp_f32_e32 v115, v115
	v_add_f32_e32 v169, v169, v113
	v_cvt_pk_bf16_f32 v184, v112, v113
	v_mfma_f32_32x32x16_bf16 v[80:95], v[206:209], v[104:107], v[80:95]
	ds_read_b128 v[206:209], v210 offset:4096
	v_exp_f32_e32 v116, v116
	v_add_f32_e32 v169, v169, v114
	v_exp_f32_e32 v117, v117
	v_mfma_f32_32x32x16_bf16 v[80:95], v[150:153], v[108:111], v[80:95]
	ds_read_b128 v[150:153], v211 offset:4096
	v_add_f32_e32 v169, v169, v115
	v_cvt_pk_bf16_f32 v185, v114, v115
	v_exp_f32_e32 v118, v118
	v_add_f32_e32 v169, v169, v116
	s_waitcnt lgkmcnt(10)
	v_mfma_f32_32x32x16_bf16 v[0:15], v[154:157], v[176:179], v[0:15]
	ds_read_b64_tr_b16 v[154:155], v142 offset:12288
	ds_read_b64_tr_b16 v[156:157], v142 offset:14336
	v_exp_f32_e32 v119, v119
	v_add_f32_e32 v169, v169, v117
	v_cvt_pk_bf16_f32 v186, v116, v117
	v_exp_f32_e32 v120, v120
	s_waitcnt lgkmcnt(10)
	v_mfma_f32_32x32x16_bf16 v[16:31], v[158:161], v[176:179], v[16:31]
	ds_read_b64_tr_b16 v[158:159], v143 offset:12288
	ds_read_b64_tr_b16 v[160:161], v143 offset:14336
	v_add_f32_e32 v169, v169, v118
	v_exp_f32_e32 v121, v121
	v_add_f32_e32 v169, v169, v119
	s_waitcnt lgkmcnt(10)
	v_mfma_f32_32x32x16_bf16 v[48:63], v[162:165], v[176:179], v[48:63]
	ds_read_b64_tr_b16 v[162:163], v146 offset:12288
	ds_read_b64_tr_b16 v[164:165], v146 offset:14336
	v_cvt_pk_bf16_f32 v187, v118, v119
	v_exp_f32_e32 v122, v122
	v_add_f32_e32 v169, v169, v120
	v_exp_f32_e32 v123, v123
	s_waitcnt lgkmcnt(10)
; template <int DV>
; __device__ __forceinline__ void attn_pass(const int tid, unsigned char* smem, const bf16_t* Q0, int qpitch, const bf16_t* Kb, int kpitch, const bf16_t* Vb, int vpitch,
;                                           int b, int ntiles, float kmax, f32x16 (&o)[DV / 32], float& linv) {
;     ...
;     for (int kt = 0; kt < ntiles; ++kt) {
;         if (kt + 1 < ntiles) gload(kt + 1);
;         const unsigned char* Ks = smem + (kt & 1) * BUF; const unsigned char* Vs = Ks + KBYTES;
;         const unsigned char* kp = Ks + r32 * KP + hi * 16;
;         bf16x8 pf[2][2];
; #pragma unroll
;         for (int kb = 0; kb < 2; ++kb) {
;             f32x16 s;
; #pragma unroll
;             for (int r = 0; r < 16; ++r) s[r] = nshift;
; #pragma unroll
;             for (int ds = 0; ds < 4; ++ds) {
;                 const bf16x8 kf = *(const bf16x8*)(kp + kb * 32 * KP + ds * 32);
;                 s = __builtin_amdgcn_mfma_f32_32x32x16_bf16(kf, qf[ds], s, 0, 0, 0);
;             }
;             float ls = 0.f;
; #pragma unroll
;             for (int r = 0; r < 16; ++r) { s[r] = __builtin_amdgcn_exp2f(s[r]); ls += s[r]; }
;             lsum += ls;
; #pragma unroll
;             for (int j = 0; j < 2; ++j) {
;                 u32x4 w0;
;                 w0.x = cvt_pk_bf16(s[8 * j + 0], s[8 * j + 1]); w0.y = cvt_pk_bf16(s[8 * j + 2], s[8 * j + 3]); w0.z = cvt_pk_bf16(s[8 * j + 4], s[8 * j + 5]); w0.w = cvt_pk_bf16(s[8 * j + 6], s[8 * j + 7]);
;                 pf[kb][j] = __builtin_bit_cast(bf16x8, w0);
;             }
;         }
;         const unsigned char* vp = Vs + (4 * hi + q4) * VP + (16 * nhalf + 4 * p4) * 2;
; #pragma unroll
;         for (int d0 = 0; d0 < DV / 32; ++d0) {
; #pragma unroll
;             for (int kb = 0; kb < 2; ++kb)
; #pragma unroll
;                 for (int j = 0; j < 2; ++j) {
;                     const unsigned char* a = vp + (32 * kb + 16 * j) * VP + d0 * 64;
;                     const s16x4 lo = ld_tr(a), h4 = ld_tr(a + 8 * VP);
;                     const bf16x8 vf = (bf16x8){lo[0], lo[1], lo[2], lo[3], h4[0], h4[1], h4[2], h4[3]};
;                     o[d0] = __builtin_amdgcn_mfma_f32_32x32x16_bf16(vf, pf[kb][j], o[d0], 0, 0, 0);
;                 }
;             if (d0 & 1) __builtin_amdgcn_sched_barrier(0);
;         }
;         if (kt + 1 < ntiles) lwrite((kt + 1) & 1);
;         __syncthreads();
;     }
	v_mfma_f32_32x32x16_bf16 v[64:79], v[230:233], v[176:179], v[64:79]
	ds_read_b64_tr_b16 v[230:231], v147 offset:12288
	ds_read_b64_tr_b16 v[232:233], v147 offset:14336
	s_and_b32 s2, s59, 3
	s_cmp_eq_u32 s2, 3
	s_cselect_b32 s2, 0x18000, 0
	s_sub_i32 s58, 0x6000, s2
	v_add_f32_e32 v169, v169, v121
	v_cvt_pk_bf16_f32 v188, v120, v121
	v_exp_f32_e32 v124, v124
	s_waitcnt lgkmcnt(6)
	v_mfma_f32_32x32x16_bf16 v[0:15], v[154:157], v[180:183], v[0:15]
	ds_read_b64_tr_b16 v[154:155], v142 offset:16384
	ds_read_b64_tr_b16 v[156:157], v142 offset:18432
	v_add_u32_e32 v174, s58, v174
	v_add_u32_e32 v175, s58, v175
	v_add_u32_e32 v210, s58, v210
	v_add_u32_e32 v211, s58, v211
	v_add_f32_e32 v169, v169, v122
	v_exp_f32_e32 v125, v125
	v_add_f32_e32 v169, v169, v123
	v_cvt_pk_bf16_f32 v189, v122, v123
	s_waitcnt lgkmcnt(6)
	v_mfma_f32_32x32x16_bf16 v[16:31], v[158:161], v[180:183], v[16:31]
	ds_read_b64_tr_b16 v[158:159], v143 offset:16384
	ds_read_b64_tr_b16 v[160:161], v143 offset:18432
	v_exp_f32_e32 v126, v126
	v_add_f32_e32 v169, v169, v124
	v_exp_f32_e32 v127, v127
	s_waitcnt lgkmcnt(6)
	v_mfma_f32_32x32x16_bf16 v[48:63], v[162:165], v[180:183], v[48:63]
	ds_read_b64_tr_b16 v[162:163], v146 offset:16384
	ds_read_b64_tr_b16 v[164:165], v146 offset:18432
	v_add_f32_e32 v169, v169, v125
	v_cvt_pk_bf16_f32 v190, v124, v125
	v_add_f32_e32 v169, v169, v126
	v_add_f32_e32 v169, v169, v127
	v_cvt_pk_bf16_f32 v191, v126, v127
	s_waitcnt lgkmcnt(6)
	v_mfma_f32_32x32x16_bf16 v[64:79], v[230:233], v[180:183], v[64:79]
	ds_read_b64_tr_b16 v[230:231], v147 offset:16384
	ds_read_b64_tr_b16 v[232:233], v147 offset:18432
	v_mfma_f32_32x32x16_bf16 v[112:127], v[198:201], v[96:99], v[32:47]
	v_exp_f32_e32 v80, v80
	v_exp_f32_e32 v81, v81
	v_exp_f32_e32 v82, v82
	v_mfma_f32_32x32x16_bf16 v[112:127], v[202:205], v[100:103], v[112:127]
	v_add_f32_e32 v169, v169, v80
	v_exp_f32_e32 v83, v83
	v_add_f32_e32 v169, v169, v81
	v_cvt_pk_bf16_f32 v176, v80, v81
	v_mfma_f32_32x32x16_bf16 v[112:127], v[206:209], v[104:107], v[112:127]
	v_exp_f32_e32 v84, v84
	v_add_f32_e32 v169, v169, v82
	v_exp_f32_e32 v85, v85
	v_mfma_f32_32x32x16_bf16 v[112:127], v[150:153], v[108:111], v[112:127]
	v_add_f32_e32 v169, v169, v83
	v_cvt_pk_bf16_f32 v177, v82, v83
	v_exp_f32_e32 v86, v86
	v_add_f32_e32 v169, v169, v84
	s_waitcnt lgkmcnt(6)
	v_mfma_f32_32x32x16_bf16 v[0:15], v[154:157], v[184:187], v[0:15]
	ds_read_b64_tr_b16 v[154:155], v142 offset:20480
	ds_read_b64_tr_b16 v[156:157], v142 offset:22528
	v_exp_f32_e32 v87, v87
	v_add_f32_e32 v169, v169, v85
	v_cvt_pk_bf16_f32 v178, v84, v85
	v_exp_f32_e32 v88, v88
	s_waitcnt lgkmcnt(6)
	v_mfma_f32_32x32x16_bf16 v[16:31], v[158:161], v[184:187], v[16:31]
	ds_read_b64_tr_b16 v[158:159], v143 offset:20480
	ds_read_b64_tr_b16 v[160:161], v143 offset:22528
	v_add_f32_e32 v169, v169, v86
	v_exp_f32_e32 v89, v89
	v_add_f32_e32 v169, v169, v87
	s_waitcnt lgkmcnt(6)
	v_mfma_f32_32x32x16_bf16 v[48:63], v[162:165], v[184:187], v[48:63]
	ds_read_b64_tr_b16 v[162:163], v146 offset:20480
	ds_read_b64_tr_b16 v[164:165], v146 offset:22528
	v_cvt_pk_bf16_f32 v179, v86, v87
	v_exp_f32_e32 v90, v90
	v_add_f32_e32 v169, v169, v88
	v_exp_f32_e32 v91, v91
	s_waitcnt lgkmcnt(6)
	v_mfma_f32_32x32x16_bf16 v[64:79], v[230:233], v[184:187], v[64:79]
	ds_read_b64_tr_b16 v[230:231], v147 offset:20480
	ds_read_b64_tr_b16 v[232:233], v147 offset:22528
	v_add_u32_e32 v142, s58, v142
	v_add_u32_e32 v143, s58, v143
	v_add_u32_e32 v146, s58, v146
	v_add_u32_e32 v147, s58, v147
	v_add_f32_e32 v169, v169, v89
	v_cvt_pk_bf16_f32 v180, v88, v89
	v_exp_f32_e32 v92, v92
	s_waitcnt lgkmcnt(6)
	v_mfma_f32_32x32x16_bf16 v[0:15], v[154:157], v[188:191], v[0:15]
	ds_read_b64_tr_b16 v[154:155], v142 offset:8192
	ds_read_b64_tr_b16 v[156:157], v142 offset:10240
	v_add_f32_e32 v169, v169, v90
	v_exp_f32_e32 v93, v93
	v_add_f32_e32 v169, v169, v91
	v_cvt_pk_bf16_f32 v181, v90, v91
	s_waitcnt lgkmcnt(6)
	v_mfma_f32_32x32x16_bf16 v[16:31], v[158:161], v[188:191], v[16:31]
	ds_read_b64_tr_b16 v[158:159], v143 offset:8192
	ds_read_b64_tr_b16 v[160:161], v143 offset:10240
	v_exp_f32_e32 v94, v94
	v_add_f32_e32 v169, v169, v92
	v_exp_f32_e32 v95, v95
	s_waitcnt lgkmcnt(6)
	v_mfma_f32_32x32x16_bf16 v[48:63], v[162:165], v[188:191], v[48:63]
	ds_read_b64_tr_b16 v[162:163], v146 offset:8192
	ds_read_b64_tr_b16 v[164:165], v146 offset:10240
	s_add_i32 s59, s59, 1
	v_add_f32_e32 v169, v169, v93
	v_cvt_pk_bf16_f32 v182, v92, v93
	v_add_f32_e32 v169, v169, v94
	v_add_f32_e32 v169, v169, v95
	v_cvt_pk_bf16_f32 v183, v94, v95
	s_waitcnt lgkmcnt(6)
	v_mfma_f32_32x32x16_bf16 v[64:79], v[230:233], v[188:191], v[64:79]
	ds_read_b64_tr_b16 v[230:231], v147 offset:8192
	ds_read_b64_tr_b16 v[232:233], v147 offset:10240
	s_waitcnt lgkmcnt(8)
	s_barrier
; __device__ __forceinline__ s16x4 ld_tr(const unsigned char* p) { return __builtin_bit_cast(s16x4, __builtin_amdgcn_ds_read_tr16_b64_v4i16((LAS s16x4*)p)); }
; template <int DV>
; __device__ __forceinline__ void attn_pass(const int tid, unsigned char* smem, const bf16_t* Q0, int qpitch, const bf16_t* Kb, int kpitch, const bf16_t* Vb, int vpitch,
;                                           int b, int ntiles, float kmax, f32x16 (&o)[DV / 32], float& linv) {
;     ...
;         const unsigned char* vp = Vs + (4 * hi + q4) * VP + (16 * nhalf + 4 * p4) * 2;
; #pragma unroll
;         for (int d0 = 0; d0 < DV / 32; ++d0) {
; #pragma unroll
;             for (int kb = 0; kb < 2; ++kb)
; #pragma unroll
;                 for (int j = 0; j < 2; ++j) {
;                     const unsigned char* a = vp + (32 * kb + 16 * j) * VP + d0 * 64;
;                     const s16x4 lo = ld_tr(a), h4 = ld_tr(a + 8 * VP);
;                     const bf16x8 vf = (bf16x8){lo[0], lo[1], lo[2], lo[3], h4[0], h4[1], h4[2], h4[3]};
;                     o[d0] = __builtin_amdgcn_mfma_f32_32x32x16_bf16(vf, pf[kb][j], o[d0], 0, 0, 0);
;                 }
;             if (d0 & 1) __builtin_amdgcn_sched_barrier(0);
;         }
;         if (kt + 1 < ntiles) lwrite((kt + 1) & 1);
;         __syncthreads();
;     }
	s_waitcnt lgkmcnt(6)
	v_mfma_f32_32x32x16_bf16 v[0:15], v[154:157], v[176:179], v[0:15]
	ds_read_b64_tr_b16 v[154:155], v142 offset:12288
	ds_read_b64_tr_b16 v[156:157], v142 offset:14336
	v_exp_f32_e32 v112, v112
	v_exp_f32_e32 v113, v113
	v_exp_f32_e32 v114, v114
	v_add_f32_e32 v169, v169, v112
	v_exp_f32_e32 v115, v115
	s_waitcnt lgkmcnt(6)
	v_mfma_f32_32x32x16_bf16 v[16:31], v[158:161], v[176:179], v[16:31]
	ds_read_b64_tr_b16 v[158:159], v143 offset:12288
	ds_read_b64_tr_b16 v[160:161], v143 offset:14336
	v_add_f32_e32 v169, v169, v113
	v_cvt_pk_bf16_f32 v184, v112, v113
	v_exp_f32_e32 v116, v116
	v_add_f32_e32 v169, v169, v114
	v_exp_f32_e32 v117, v117
	s_waitcnt lgkmcnt(6)
	v_mfma_f32_32x32x16_bf16 v[48:63], v[162:165], v[176:179], v[48:63]
	ds_read_b64_tr_b16 v[162:163], v146 offset:12288
	ds_read_b64_tr_b16 v[164:165], v146 offset:14336
	v_add_f32_e32 v169, v169, v115
	v_cvt_pk_bf16_f32 v185, v114, v115
	v_exp_f32_e32 v118, v118
	v_add_f32_e32 v169, v169, v116
	v_exp_f32_e32 v119, v119
	v_add_f32_e32 v169, v169, v117
	s_waitcnt lgkmcnt(6)
	v_mfma_f32_32x32x16_bf16 v[64:79], v[230:233], v[176:179], v[64:79]
	ds_read_b64_tr_b16 v[230:231], v147 offset:12288
	ds_read_b64_tr_b16 v[232:233], v147 offset:14336
	s_and_b32 s2, s59, 3
	s_cmp_eq_u32 s2, 3
	s_cselect_b32 s2, 0x18000, 0
	s_sub_i32 s58, 0x6000, s2
	v_cvt_pk_bf16_f32 v186, v116, v117
	v_exp_f32_e32 v120, v120
	v_add_f32_e32 v169, v169, v118
	v_exp_f32_e32 v121, v121
	v_add_f32_e32 v169, v169, v119
	v_cvt_pk_bf16_f32 v187, v118, v119
	s_waitcnt lgkmcnt(6)
	v_mfma_f32_32x32x16_bf16 v[0:15], v[154:157], v[180:183], v[0:15]
	ds_read_b64_tr_b16 v[154:155], v142 offset:16384
	ds_read_b64_tr_b16 v[156:157], v142 offset:18432
	v_exp_f32_e32 v122, v122
	v_add_f32_e32 v169, v169, v120
	v_exp_f32_e32 v123, v123
	v_add_f32_e32 v169, v169, v121
	v_cvt_pk_bf16_f32 v188, v120, v121
	v_exp_f32_e32 v124, v124
	s_waitcnt lgkmcnt(6)
	v_mfma_f32_32x32x16_bf16 v[16:31], v[158:161], v[180:183], v[16:31]
	ds_read_b64_tr_b16 v[158:159], v143 offset:16384
	ds_read_b64_tr_b16 v[160:161], v143 offset:18432
	v_add_f32_e32 v169, v169, v122
	v_exp_f32_e32 v125, v125
	v_add_f32_e32 v169, v169, v123
	v_cvt_pk_bf16_f32 v189, v122, v123
	v_exp_f32_e32 v126, v126
	s_waitcnt lgkmcnt(6)
	v_mfma_f32_32x32x16_bf16 v[48:63], v[162:165], v[180:183], v[48:63]
	ds_read_b64_tr_b16 v[162:163], v146 offset:16384
	ds_read_b64_tr_b16 v[164:165], v146 offset:18432
	v_add_f32_e32 v169, v169, v124
	v_exp_f32_e32 v127, v127
	v_add_f32_e32 v169, v169, v125
	v_cvt_pk_bf16_f32 v190, v124, v125
	v_add_f32_e32 v169, v169, v126
	v_add_f32_e32 v169, v169, v127
	v_cvt_pk_bf16_f32 v191, v126, v127
	s_waitcnt lgkmcnt(6)
	v_mfma_f32_32x32x16_bf16 v[64:79], v[230:233], v[180:183], v[64:79]
	ds_read_b64_tr_b16 v[230:231], v147 offset:16384
	ds_read_b64_tr_b16 v[232:233], v147 offset:18432
	s_waitcnt lgkmcnt(6)
	v_mfma_f32_32x32x16_bf16 v[0:15], v[154:157], v[184:187], v[0:15]
	ds_read_b64_tr_b16 v[154:155], v142 offset:20480
	ds_read_b64_tr_b16 v[156:157], v142 offset:22528
	s_waitcnt lgkmcnt(6)
	v_mfma_f32_32x32x16_bf16 v[16:31], v[158:161], v[184:187], v[16:31]
	ds_read_b64_tr_b16 v[158:159], v143 offset:20480
	ds_read_b64_tr_b16 v[160:161], v143 offset:22528
	s_waitcnt lgkmcnt(6)
	v_mfma_f32_32x32x16_bf16 v[48:63], v[162:165], v[184:187], v[48:63]
	ds_read_b64_tr_b16 v[162:163], v146 offset:20480
	ds_read_b64_tr_b16 v[164:165], v146 offset:22528
	s_waitcnt lgkmcnt(6)
	v_mfma_f32_32x32x16_bf16 v[64:79], v[230:233], v[184:187], v[64:79]
	ds_read_b64_tr_b16 v[230:231], v147 offset:20480
	ds_read_b64_tr_b16 v[232:233], v147 offset:22528
	s_waitcnt lgkmcnt(6)
	v_mfma_f32_32x32x16_bf16 v[0:15], v[154:157], v[188:191], v[0:15]
	s_waitcnt lgkmcnt(4)
	v_mfma_f32_32x32x16_bf16 v[16:31], v[158:161], v[188:191], v[16:31]
	s_waitcnt lgkmcnt(2)
	v_mfma_f32_32x32x16_bf16 v[48:63], v[162:165], v[188:191], v[48:63]
	s_waitcnt lgkmcnt(0)
	v_mfma_f32_32x32x16_bf16 v[64:79], v[230:233], v[188:191], v[64:79]
	s_waitcnt lgkmcnt(0)
	s_barrier
	s_waitcnt vmcnt(0)
